# FFN epilogue conv+gate section hand-scheduled (same arithmetic/order per element, no hazard padding, fewer moves)
# speedup vs baseline: 1.0055x; 1.0055x over previous
;     __device__ __forceinline__ void operator()(f32x4 (&acc)[2][2][4][2], const Unit& u, int wr, int wc, int fr, int fq, int next_pn) const {
;     ...
;         int rowb = u.pm * BM + rl0; asm volatile("" : "+v"(rowb));
; #pragma unroll
;         for (int ai = 0; ai < 2; ++ai) { const int sl = 2 * ai + wr;
;             u32x2 keep[4];
; #pragma unroll
;             for (int hf = 0; hf < 2; ++hf) {
;                 __builtin_amdgcn_sched_barrier(0);
;                 const LAS float* wl = WL + tcol + 4 * hf;
;                 const f32x4 wg0 = *(const LAS f32x4*)(wl), wg1 = *(const LAS f32x4*)(wl + 256), wg2 = *(const LAS f32x4*)(wl + 512), bg = *(const LAS f32x4*)(wl + 768);
;                 const f32x4 wv0 = *(const LAS f32x4*)(wl + 128), wv1 = *(const LAS f32x4*)(wl + 384), wv2 = *(const LAS f32x4*)(wl + 640), bvv = *(const LAS f32x4*)(wl + 896);
;                 f32x4 hg62 = (f32x4){0.f, 0.f, 0.f, 0.f}, hg63 = hg62, hv62 = hg62, hv63 = hg62;
;                 if (sl > 0) { const LAS float* hp = H + ((sl - 1) * 2) * 256 + tcol + 4 * hf; hg62 = *(const LAS f32x4*)hp; hv62 = *(const LAS f32x4*)(hp + 128); hg63 = *(const LAS f32x4*)(hp + 256); hv63 = *(const LAS f32x4*)(hp + 384); }
;                 f32x4 sg3, sg2, sv3, sv2;
; #pragma unroll
;                 for (int j = 0; j < 4; ++j) { sg3[j] = dpp_shr1(hg63[j], acc[ai][0][3][hf][j]); sg2[j] = dpp_shr1(hg62[j], acc[ai][0][2][hf][j]); sv3[j] = dpp_shr1(hv63[j], acc[ai][1][3][hf][j]); sv2[j] = dpp_shr1(hv62[j], acc[ai][1][2][hf][j]); }
; #pragma unroll
;                 for (int m = 0; m < 4; ++m) {
;                     const f32x4 cg = acc[ai][0][m][hf], cv = acc[ai][1][m][hf];
;                     const f32x4 g1v = (m == 0) ? sg3 : acc[ai][0][m == 0 ? 0 : m - 1][hf], g2v = (m == 0) ? sg2 : (m == 1) ? sg3 : acc[ai][0][m < 2 ? 0 : m - 2][hf];
;                     const f32x4 v1v = (m == 0) ? sv3 : acc[ai][1][m == 0 ? 0 : m - 1][hf], v2v = (m == 0) ? sv2 : (m == 1) ? sv3 : acc[ai][1][m < 2 ? 0 : m - 2][hf];
;                     float o[4];
; #pragma unroll
;                     for (int j2 = 0; j2 < 2; ++j2) {
;                         const int j = 2 * j2;
;                         const f32x2v g1 = {g1v[j], g1v[j + 1]}, g2 = {g2v[j], g2v[j + 1]}, v1 = {v1v[j], v1v[j + 1]}, v2 = {v2v[j], v2v[j + 1]};
;                         const f32x2v c_g = {cg[j], cg[j + 1]}, c_v = {cv[j], cv[j + 1]};
.LBB0_737:
	s_waitcnt lgkmcnt(0)
	s_barrier
	v_lshl_add_u32 v196, s89, 8, v140
	v_lshl_add_u32 v197, v0, 2, s8
	v_lshl_add_u32 v198, v0, 2, s79
	v_lshl_add_u32 v199, v0, 2, s85
	v_mov_b64_e32 v[214:215], s[70:71]
	v_lshlrev_b64 v[212:213], 1, v[202:203]
	s_mov_b32 s98, 0x1600
	s_mov_b32 s99, 0
	v_mad_i64_i32 v[210:211], s[8:9], v196, s77, v[214:215]
	v_lshl_add_u64 v[210:211], v[210:211], 0, v[212:213]
	ds_read_b128 v[130:133], v197 offset:0
	ds_read_b128 v[134:137], v197 offset:512
	ds_read_b128 v[138:141], v197 offset:1024
	ds_read_b128 v[142:145], v197 offset:1536
	ds_read_b128 v[146:149], v197 offset:2048
	ds_read_b128 v[150:153], v197 offset:2560
	ds_read_b128 v[154:157], v197 offset:3072
	ds_read_b128 v[158:161], v197 offset:3584
	s_and_b64 vcc, exec, s[34:35]
	s_cbranch_vccz .Lffn_hz_1
	ds_read_b128 v[162:165], v198 offset:0
	ds_read_b128 v[166:169], v198 offset:512
	ds_read_b128 v[170:173], v198 offset:1024
	ds_read_b128 v[174:177], v198 offset:1536
	s_branch .Lffn_hj_1
.Lffn_hz_1:
	v_mov_b32_e32 v162, 0
	v_mov_b32_e32 v163, 0
	v_mov_b32_e32 v164, 0
	v_mov_b32_e32 v165, 0
	v_mov_b32_e32 v166, 0
	v_mov_b32_e32 v167, 0
	v_mov_b32_e32 v168, 0
	v_mov_b32_e32 v169, 0
	v_mov_b32_e32 v170, 0
	v_mov_b32_e32 v171, 0
	v_mov_b32_e32 v172, 0
	v_mov_b32_e32 v173, 0
	v_mov_b32_e32 v174, 0
	v_mov_b32_e32 v175, 0
	v_mov_b32_e32 v176, 0
	v_mov_b32_e32 v177, 0
.Lffn_hj_1:
	s_waitcnt lgkmcnt(0)
	v_mov_b32_dpp v170, v126 row_shr:1 row_mask:0xf bank_mask:0xf
	v_mov_b32_dpp v162, v114 row_shr:1 row_mask:0xf bank_mask:0xf
	v_mov_b32_dpp v174, v122 row_shr:1 row_mask:0xf bank_mask:0xf
	v_mov_b32_dpp v166, v118 row_shr:1 row_mask:0xf bank_mask:0xf
	v_mov_b32_dpp v171, v127 row_shr:1 row_mask:0xf bank_mask:0xf
	v_mov_b32_dpp v163, v115 row_shr:1 row_mask:0xf bank_mask:0xf
	v_mov_b32_dpp v175, v123 row_shr:1 row_mask:0xf bank_mask:0xf
	v_mov_b32_dpp v167, v119 row_shr:1 row_mask:0xf bank_mask:0xf
	v_mov_b32_dpp v172, v128 row_shr:1 row_mask:0xf bank_mask:0xf
	v_mov_b32_dpp v164, v116 row_shr:1 row_mask:0xf bank_mask:0xf
	v_mov_b32_dpp v176, v124 row_shr:1 row_mask:0xf bank_mask:0xf
	v_mov_b32_dpp v168, v120 row_shr:1 row_mask:0xf bank_mask:0xf
	v_mov_b32_dpp v173, v129 row_shr:1 row_mask:0xf bank_mask:0xf
	v_mov_b32_dpp v165, v117 row_shr:1 row_mask:0xf bank_mask:0xf
	v_mov_b32_dpp v177, v125 row_shr:1 row_mask:0xf bank_mask:0xf
	v_mov_b32_dpp v169, v121 row_shr:1 row_mask:0xf bank_mask:0xf
	v_pk_fma_f32 v[214:215], v[110:111], v[146:147], v[154:155]
	v_pk_fma_f32 v[220:221], v[112:113], v[148:149], v[156:157]
	v_pk_fma_f32 v[216:217], v[102:103], v[150:151], v[158:159]
	v_pk_fma_f32 v[222:223], v[104:105], v[152:153], v[160:161]
	v_pk_fma_f32 v[214:215], v[138:139], v[170:171], v[214:215]
	v_pk_fma_f32 v[220:221], v[140:141], v[172:173], v[220:221]
	v_pk_fma_f32 v[216:217], v[142:143], v[174:175], v[216:217]
	v_pk_fma_f32 v[222:223], v[144:145], v[176:177], v[222:223]
	v_pk_fma_f32 v[214:215], v[130:131], v[162:163], v[214:215]
	v_pk_fma_f32 v[220:221], v[132:133], v[164:165], v[220:221]
	v_pk_fma_f32 v[216:217], v[134:135], v[166:167], v[216:217]
	v_pk_fma_f32 v[222:223], v[136:137], v[168:169], v[222:223]
	v_pk_mul_f32 v[218:219], v[214:215], s[88:89] op_sel_hi:[1,0]
	v_pk_mul_f32 v[224:225], v[220:221], s[88:89] op_sel_hi:[1,0]
	v_exp_f32_e32 v218, v218
	v_exp_f32_e32 v224, v224
	v_exp_f32_e32 v219, v219
	v_exp_f32_e32 v225, v225
	v_pk_add_f32 v[218:219], v[218:219], 1.0 op_sel_hi:[1,0]
	v_pk_add_f32 v[224:225], v[224:225], 1.0 op_sel_hi:[1,0]
	v_rcp_f32_e32 v218, v218
	v_rcp_f32_e32 v224, v224
	v_rcp_f32_e32 v219, v219
	v_rcp_f32_e32 v225, v225
	v_pk_mul_f32 v[214:215], v[214:215], v[218:219]
	v_pk_mul_f32 v[220:221], v[220:221], v[224:225]
	v_pk_mul_f32 v[214:215], v[216:217], v[214:215]
	v_pk_mul_f32 v[220:221], v[222:223], v[220:221]
	v_cvt_pk_bf16_f32 v226, v214, v215
	v_cvt_pk_bf16_f32 v227, v220, v221
	v_pk_fma_f32 v[214:215], v[94:95], v[146:147], v[154:155]
	v_pk_fma_f32 v[220:221], v[96:97], v[148:149], v[156:157]
	v_pk_fma_f32 v[216:217], v[86:87], v[150:151], v[158:159]
	v_pk_fma_f32 v[222:223], v[88:89], v[152:153], v[160:161]
	v_pk_fma_f32 v[214:215], v[138:139], v[110:111], v[214:215]
	v_pk_fma_f32 v[220:221], v[140:141], v[112:113], v[220:221]
	v_pk_fma_f32 v[216:217], v[142:143], v[102:103], v[216:217]
	v_pk_fma_f32 v[222:223], v[144:145], v[104:105], v[222:223]
	v_pk_fma_f32 v[214:215], v[130:131], v[170:171], v[214:215]
;     __device__ __forceinline__ void operator()(f32x4 (&acc)[2][2][4][2], const Unit& u, int wr, int wc, int fr, int fq, int next_pn) const {
;     ...
;             for (int hf = 0; hf < 2; ++hf) {
;                 __builtin_amdgcn_sched_barrier(0);
;                 const LAS float* wl = WL + tcol + 4 * hf;
;                 const f32x4 wg0 = *(const LAS f32x4*)(wl), wg1 = *(const LAS f32x4*)(wl + 256), wg2 = *(const LAS f32x4*)(wl + 512), bg = *(const LAS f32x4*)(wl + 768);
;                 const f32x4 wv0 = *(const LAS f32x4*)(wl + 128), wv1 = *(const LAS f32x4*)(wl + 384), wv2 = *(const LAS f32x4*)(wl + 640), bvv = *(const LAS f32x4*)(wl + 896);
;                 f32x4 hg62 = (f32x4){0.f, 0.f, 0.f, 0.f}, hg63 = hg62, hv62 = hg62, hv63 = hg62;
;                 if (sl > 0) { const LAS float* hp = H + ((sl - 1) * 2) * 256 + tcol + 4 * hf; hg62 = *(const LAS f32x4*)hp; hv62 = *(const LAS f32x4*)(hp + 128); hg63 = *(const LAS f32x4*)(hp + 256); hv63 = *(const LAS f32x4*)(hp + 384); }
;                 f32x4 sg3, sg2, sv3, sv2;
; #pragma unroll
;                 for (int j = 0; j < 4; ++j) { sg3[j] = dpp_shr1(hg63[j], acc[ai][0][3][hf][j]); sg2[j] = dpp_shr1(hg62[j], acc[ai][0][2][hf][j]); sv3[j] = dpp_shr1(hv63[j], acc[ai][1][3][hf][j]); sv2[j] = dpp_shr1(hv62[j], acc[ai][1][2][hf][j]); }
; #pragma unroll
;                 for (int m = 0; m < 4; ++m) {
;                     const f32x4 cg = acc[ai][0][m][hf], cv = acc[ai][1][m][hf];
;                     const f32x4 g1v = (m == 0) ? sg3 : acc[ai][0][m == 0 ? 0 : m - 1][hf], g2v = (m == 0) ? sg2 : (m == 1) ? sg3 : acc[ai][0][m < 2 ? 0 : m - 2][hf];
;                     const f32x4 v1v = (m == 0) ? sv3 : acc[ai][1][m == 0 ? 0 : m - 1][hf], v2v = (m == 0) ? sv2 : (m == 1) ? sv3 : acc[ai][1][m < 2 ? 0 : m - 2][hf];
;                     float o[4];
; #pragma unroll
;                     for (int j2 = 0; j2 < 2; ++j2) {
;                         const int j = 2 * j2;
;                         const f32x2v g1 = {g1v[j], g1v[j + 1]}, g2 = {g2v[j], g2v[j + 1]}, v1 = {v1v[j], v1v[j + 1]}, v2 = {v2v[j], v2v[j + 1]};
;                         const f32x2v c_g = {cg[j], cg[j + 1]}, c_v = {cv[j], cv[j + 1]};
;                         const f32x2v gc = (f32x2v){wg0[j], wg0[j + 1]} * g2 + ((f32x2v){wg1[j], wg1[j + 1]} * g1 + ((f32x2v){wg2[j], wg2[j + 1]} * c_g + (f32x2v){bg[j], bg[j + 1]}));
	v_pk_fma_f32 v[220:221], v[132:133], v[172:173], v[220:221]
	v_pk_fma_f32 v[216:217], v[134:135], v[174:175], v[216:217]
	v_pk_fma_f32 v[222:223], v[136:137], v[176:177], v[222:223]
	v_pk_mul_f32 v[218:219], v[214:215], s[88:89] op_sel_hi:[1,0]
	v_pk_mul_f32 v[224:225], v[220:221], s[88:89] op_sel_hi:[1,0]
	v_exp_f32_e32 v218, v218
	v_exp_f32_e32 v224, v224
	v_exp_f32_e32 v219, v219
	v_exp_f32_e32 v225, v225
	v_pk_add_f32 v[218:219], v[218:219], 1.0 op_sel_hi:[1,0]
	v_pk_add_f32 v[224:225], v[224:225], 1.0 op_sel_hi:[1,0]
	v_rcp_f32_e32 v218, v218
	v_rcp_f32_e32 v224, v224
	v_rcp_f32_e32 v219, v219
	v_rcp_f32_e32 v225, v225
	v_pk_mul_f32 v[214:215], v[214:215], v[218:219]
	v_pk_mul_f32 v[220:221], v[220:221], v[224:225]
	v_pk_mul_f32 v[214:215], v[216:217], v[214:215]
	v_pk_mul_f32 v[220:221], v[222:223], v[220:221]
	v_cvt_pk_bf16_f32 v230, v214, v215
	v_cvt_pk_bf16_f32 v231, v220, v221
	v_pk_fma_f32 v[214:215], v[114:115], v[146:147], v[154:155]
	v_pk_fma_f32 v[220:221], v[116:117], v[148:149], v[156:157]
	v_pk_fma_f32 v[216:217], v[118:119], v[150:151], v[158:159]
	v_pk_fma_f32 v[222:223], v[120:121], v[152:153], v[160:161]
	v_pk_fma_f32 v[214:215], v[138:139], v[94:95], v[214:215]
	v_pk_fma_f32 v[220:221], v[140:141], v[96:97], v[220:221]
	v_pk_fma_f32 v[216:217], v[142:143], v[86:87], v[216:217]
	v_pk_fma_f32 v[222:223], v[144:145], v[88:89], v[222:223]
	v_pk_fma_f32 v[214:215], v[130:131], v[110:111], v[214:215]
	v_pk_fma_f32 v[220:221], v[132:133], v[112:113], v[220:221]
	v_pk_fma_f32 v[216:217], v[134:135], v[102:103], v[216:217]
	v_pk_fma_f32 v[222:223], v[136:137], v[104:105], v[222:223]
	v_pk_mul_f32 v[218:219], v[214:215], s[88:89] op_sel_hi:[1,0]
	v_pk_mul_f32 v[224:225], v[220:221], s[88:89] op_sel_hi:[1,0]
	v_exp_f32_e32 v218, v218
	v_exp_f32_e32 v224, v224
	v_exp_f32_e32 v219, v219
	v_exp_f32_e32 v225, v225
	v_pk_add_f32 v[218:219], v[218:219], 1.0 op_sel_hi:[1,0]
	v_pk_add_f32 v[224:225], v[224:225], 1.0 op_sel_hi:[1,0]
	v_rcp_f32_e32 v218, v218
	v_rcp_f32_e32 v224, v224
	v_rcp_f32_e32 v219, v219
	v_rcp_f32_e32 v225, v225
	v_pk_mul_f32 v[214:215], v[214:215], v[218:219]
	v_pk_mul_f32 v[220:221], v[220:221], v[224:225]
	v_pk_mul_f32 v[214:215], v[216:217], v[214:215]
	v_pk_mul_f32 v[220:221], v[222:223], v[220:221]
	v_cvt_pk_bf16_f32 v234, v214, v215
	v_cvt_pk_bf16_f32 v235, v220, v221
	v_pk_fma_f32 v[214:215], v[126:127], v[146:147], v[154:155]
	v_pk_fma_f32 v[220:221], v[128:129], v[148:149], v[156:157]
	v_pk_fma_f32 v[216:217], v[122:123], v[150:151], v[158:159]
	v_pk_fma_f32 v[222:223], v[124:125], v[152:153], v[160:161]
	v_pk_fma_f32 v[214:215], v[138:139], v[114:115], v[214:215]
	v_pk_fma_f32 v[220:221], v[140:141], v[116:117], v[220:221]
	v_pk_fma_f32 v[216:217], v[142:143], v[118:119], v[216:217]
	v_pk_fma_f32 v[222:223], v[144:145], v[120:121], v[222:223]
	v_pk_fma_f32 v[214:215], v[130:131], v[94:95], v[214:215]
	v_pk_fma_f32 v[220:221], v[132:133], v[96:97], v[220:221]
	v_pk_fma_f32 v[216:217], v[134:135], v[86:87], v[216:217]
	v_pk_fma_f32 v[222:223], v[136:137], v[88:89], v[222:223]
	v_pk_mul_f32 v[218:219], v[214:215], s[88:89] op_sel_hi:[1,0]
	v_pk_mul_f32 v[224:225], v[220:221], s[88:89] op_sel_hi:[1,0]
	v_exp_f32_e32 v218, v218
	v_exp_f32_e32 v224, v224
	v_exp_f32_e32 v219, v219
	v_exp_f32_e32 v225, v225
	v_pk_add_f32 v[218:219], v[218:219], 1.0 op_sel_hi:[1,0]
	v_pk_add_f32 v[224:225], v[224:225], 1.0 op_sel_hi:[1,0]
	v_rcp_f32_e32 v218, v218
	v_rcp_f32_e32 v224, v224
	v_rcp_f32_e32 v219, v219
	v_rcp_f32_e32 v225, v225
	v_pk_mul_f32 v[214:215], v[214:215], v[218:219]
	v_pk_mul_f32 v[220:221], v[220:221], v[224:225]
	v_pk_mul_f32 v[214:215], v[216:217], v[214:215]
	v_pk_mul_f32 v[220:221], v[222:223], v[220:221]
	v_cvt_pk_bf16_f32 v110, v214, v215
	v_cvt_pk_bf16_f32 v111, v220, v221
	ds_read_b128 v[130:133], v197 offset:16
	ds_read_b128 v[134:137], v197 offset:528
	ds_read_b128 v[138:141], v197 offset:1040
	ds_read_b128 v[142:145], v197 offset:1552
	ds_read_b128 v[146:149], v197 offset:2064
	ds_read_b128 v[150:153], v197 offset:2576
	ds_read_b128 v[154:157], v197 offset:3088
	ds_read_b128 v[158:161], v197 offset:3600
	s_and_b64 vcc, exec, s[34:35]
	s_cbranch_vccz .Lffn_hz_2
	ds_read_b128 v[162:165], v198 offset:16
	ds_read_b128 v[166:169], v198 offset:528
	ds_read_b128 v[170:173], v198 offset:1040
	ds_read_b128 v[174:177], v198 offset:1552
	s_branch .Lffn_hj_2

;     __device__ __forceinline__ void operator()(f32x4 (&acc)[2][2][4][2], const Unit& u, int wr, int wc, int fr, int fq, int next_pn) const {
;     ...
;                 for (int j = 0; j < 4; ++j) { sg3[j] = dpp_shr1(hg63[j], acc[ai][0][3][hf][j]); sg2[j] = dpp_shr1(hg62[j], acc[ai][0][2][hf][j]); sv3[j] = dpp_shr1(hv63[j], acc[ai][1][3][hf][j]); sv2[j] = dpp_shr1(hv62[j], acc[ai][1][2][hf][j]); }
; #pragma unroll
;                 for (int m = 0; m < 4; ++m) {
;                     const f32x4 cg = acc[ai][0][m][hf], cv = acc[ai][1][m][hf];
;                     const f32x4 g1v = (m == 0) ? sg3 : acc[ai][0][m == 0 ? 0 : m - 1][hf], g2v = (m == 0) ? sg2 : (m == 1) ? sg3 : acc[ai][0][m < 2 ? 0 : m - 2][hf];
;                     const f32x4 v1v = (m == 0) ? sv3 : acc[ai][1][m == 0 ? 0 : m - 1][hf], v2v = (m == 0) ? sv2 : (m == 1) ? sv3 : acc[ai][1][m < 2 ? 0 : m - 2][hf];
;                     float o[4];
; #pragma unroll
;                     for (int j2 = 0; j2 < 2; ++j2) {
;                         const int j = 2 * j2;
;                         const f32x2v g1 = {g1v[j], g1v[j + 1]}, g2 = {g2v[j], g2v[j + 1]}, v1 = {v1v[j], v1v[j + 1]}, v2 = {v2v[j], v2v[j + 1]};
;                         const f32x2v c_g = {cg[j], cg[j + 1]}, c_v = {cv[j], cv[j + 1]};
;                         const f32x2v gc = (f32x2v){wg0[j], wg0[j + 1]} * g2 + ((f32x2v){wg1[j], wg1[j + 1]} * g1 + ((f32x2v){wg2[j], wg2[j + 1]} * c_g + (f32x2v){bg[j], bg[j + 1]}));
;                         const f32x2v vc = (f32x2v){wv0[j], wv0[j + 1]} * v2 + ((f32x2v){wv1[j], wv1[j + 1]} * v1 + ((f32x2v){wv2[j], wv2[j + 1]} * c_v + (f32x2v){bvv[j], bvv[j + 1]}));
;                         const f32x2v e = gc * (-1.4426950408889634f); f32x2v t; t.x = __builtin_amdgcn_exp2f(e.x); t.y = __builtin_amdgcn_exp2f(e.y);
;                         const f32x2v d = t + 1.0f; f32x2v r; r.x = __builtin_amdgcn_rcpf(d.x); r.y = __builtin_amdgcn_rcpf(d.y);
;                         const f32x2v oo = (gc * r) * vc; o[j] = oo.x; o[j + 1] = oo.y; }
;                     u32x2 w; w.x = cvt_pk_bf16(o[0], o[1]); w.y = cvt_pk_bf16(o[2], o[3]);
;                     if (hf == 0) keep[m] = w;
;                     else *(u32x4*)(A2 + (size_t)(rowb + ai * HALF + m) * FFW + c0) = (u32x4){keep[m].x, keep[m].y, w.x, w.y}; }
.Lffn_hj_2:
	s_waitcnt lgkmcnt(0)
	v_mov_b32_dpp v170, v70 row_shr:1 row_mask:0xf bank_mask:0xf
	v_mov_b32_dpp v162, v62 row_shr:1 row_mask:0xf bank_mask:0xf
	v_mov_b32_dpp v174, v66 row_shr:1 row_mask:0xf bank_mask:0xf
	v_mov_b32_dpp v166, v58 row_shr:1 row_mask:0xf bank_mask:0xf
	v_mov_b32_dpp v171, v71 row_shr:1 row_mask:0xf bank_mask:0xf
	v_mov_b32_dpp v163, v63 row_shr:1 row_mask:0xf bank_mask:0xf
	v_mov_b32_dpp v175, v67 row_shr:1 row_mask:0xf bank_mask:0xf
	v_mov_b32_dpp v167, v59 row_shr:1 row_mask:0xf bank_mask:0xf
	v_mov_b32_dpp v172, v72 row_shr:1 row_mask:0xf bank_mask:0xf
	v_mov_b32_dpp v164, v64 row_shr:1 row_mask:0xf bank_mask:0xf
	v_mov_b32_dpp v176, v68 row_shr:1 row_mask:0xf bank_mask:0xf
	v_mov_b32_dpp v168, v60 row_shr:1 row_mask:0xf bank_mask:0xf
	v_mov_b32_dpp v173, v73 row_shr:1 row_mask:0xf bank_mask:0xf
	v_mov_b32_dpp v165, v65 row_shr:1 row_mask:0xf bank_mask:0xf
	v_mov_b32_dpp v177, v69 row_shr:1 row_mask:0xf bank_mask:0xf
	v_mov_b32_dpp v169, v61 row_shr:1 row_mask:0xf bank_mask:0xf
	v_pk_fma_f32 v[214:215], v[106:107], v[146:147], v[154:155]
	v_pk_fma_f32 v[220:221], v[108:109], v[148:149], v[156:157]
	v_pk_fma_f32 v[216:217], v[98:99], v[150:151], v[158:159]
	v_pk_fma_f32 v[222:223], v[100:101], v[152:153], v[160:161]
	v_pk_fma_f32 v[214:215], v[138:139], v[170:171], v[214:215]
	v_pk_fma_f32 v[220:221], v[140:141], v[172:173], v[220:221]
	v_pk_fma_f32 v[216:217], v[142:143], v[174:175], v[216:217]
	v_pk_fma_f32 v[222:223], v[144:145], v[176:177], v[222:223]
	v_pk_fma_f32 v[214:215], v[130:131], v[162:163], v[214:215]
	v_pk_fma_f32 v[220:221], v[132:133], v[164:165], v[220:221]
	v_pk_fma_f32 v[216:217], v[134:135], v[166:167], v[216:217]
	v_pk_fma_f32 v[222:223], v[136:137], v[168:169], v[222:223]
	v_pk_mul_f32 v[218:219], v[214:215], s[88:89] op_sel_hi:[1,0]
	v_pk_mul_f32 v[224:225], v[220:221], s[88:89] op_sel_hi:[1,0]
	v_exp_f32_e32 v218, v218
	v_exp_f32_e32 v224, v224
	v_exp_f32_e32 v219, v219
	v_exp_f32_e32 v225, v225
	v_pk_add_f32 v[218:219], v[218:219], 1.0 op_sel_hi:[1,0]
	v_pk_add_f32 v[224:225], v[224:225], 1.0 op_sel_hi:[1,0]
	v_rcp_f32_e32 v218, v218
	v_rcp_f32_e32 v224, v224
	v_rcp_f32_e32 v219, v219
	v_rcp_f32_e32 v225, v225
	v_pk_mul_f32 v[214:215], v[214:215], v[218:219]
	v_pk_mul_f32 v[220:221], v[220:221], v[224:225]
	v_pk_mul_f32 v[214:215], v[216:217], v[214:215]
	v_pk_mul_f32 v[220:221], v[222:223], v[220:221]
	v_cvt_pk_bf16_f32 v228, v214, v215
	v_cvt_pk_bf16_f32 v229, v220, v221
	global_store_dwordx4 v[210:211], v[226:229], off
	v_lshl_add_u64 v[210:211], v[210:211], 0, s[98:99]
	v_pk_fma_f32 v[214:215], v[90:91], v[146:147], v[154:155]
	v_pk_fma_f32 v[220:221], v[92:93], v[148:149], v[156:157]
	v_pk_fma_f32 v[216:217], v[82:83], v[150:151], v[158:159]
	v_pk_fma_f32 v[222:223], v[84:85], v[152:153], v[160:161]
	v_pk_fma_f32 v[214:215], v[138:139], v[106:107], v[214:215]
	v_pk_fma_f32 v[220:221], v[140:141], v[108:109], v[220:221]
	v_pk_fma_f32 v[216:217], v[142:143], v[98:99], v[216:217]
	v_pk_fma_f32 v[222:223], v[144:145], v[100:101], v[222:223]
	v_pk_fma_f32 v[214:215], v[130:131], v[170:171], v[214:215]
	v_pk_fma_f32 v[220:221], v[132:133], v[172:173], v[220:221]
	v_pk_fma_f32 v[216:217], v[134:135], v[174:175], v[216:217]
	v_pk_fma_f32 v[222:223], v[136:137], v[176:177], v[222:223]
	v_pk_mul_f32 v[218:219], v[214:215], s[88:89] op_sel_hi:[1,0]
	v_pk_mul_f32 v[224:225], v[220:221], s[88:89] op_sel_hi:[1,0]
	v_exp_f32_e32 v218, v218
	v_exp_f32_e32 v224, v224
	v_exp_f32_e32 v219, v219
	v_exp_f32_e32 v225, v225
	v_pk_add_f32 v[218:219], v[218:219], 1.0 op_sel_hi:[1,0]
	v_pk_add_f32 v[224:225], v[224:225], 1.0 op_sel_hi:[1,0]
	v_rcp_f32_e32 v218, v218
	v_rcp_f32_e32 v224, v224
	v_rcp_f32_e32 v219, v219
	v_rcp_f32_e32 v225, v225
	v_pk_mul_f32 v[214:215], v[214:215], v[218:219]
	v_pk_mul_f32 v[220:221], v[220:221], v[224:225]
	v_pk_mul_f32 v[214:215], v[216:217], v[214:215]
	v_pk_mul_f32 v[220:221], v[222:223], v[220:221]
; #define LAS __attribute__((address_space(3)))
;     __device__ __forceinline__ void operator()(f32x4 (&acc)[2][2][4][2], const Unit& u, int wr, int wc, int fr, int fq, int next_pn) const {
;     ...
;         for (int ai = 0; ai < 2; ++ai) { const int sl = 2 * ai + wr;
;             u32x2 keep[4];
; #pragma unroll
;             for (int hf = 0; hf < 2; ++hf) {
;                 __builtin_amdgcn_sched_barrier(0);
;                 const LAS float* wl = WL + tcol + 4 * hf;
;     ...
;                 for (int m = 0; m < 4; ++m) {
;                     const f32x4 cg = acc[ai][0][m][hf], cv = acc[ai][1][m][hf];
;                     const f32x4 g1v = (m == 0) ? sg3 : acc[ai][0][m == 0 ? 0 : m - 1][hf], g2v = (m == 0) ? sg2 : (m == 1) ? sg3 : acc[ai][0][m < 2 ? 0 : m - 2][hf];
;                     const f32x4 v1v = (m == 0) ? sv3 : acc[ai][1][m == 0 ? 0 : m - 1][hf], v2v = (m == 0) ? sv2 : (m == 1) ? sv3 : acc[ai][1][m < 2 ? 0 : m - 2][hf];
;                     float o[4];
; #pragma unroll
;                     for (int j2 = 0; j2 < 2; ++j2) {
;                         const int j = 2 * j2;
;                         const f32x2v g1 = {g1v[j], g1v[j + 1]}, g2 = {g2v[j], g2v[j + 1]}, v1 = {v1v[j], v1v[j + 1]}, v2 = {v2v[j], v2v[j + 1]};
;                         const f32x2v c_g = {cg[j], cg[j + 1]}, c_v = {cv[j], cv[j + 1]};
;                         const f32x2v gc = (f32x2v){wg0[j], wg0[j + 1]} * g2 + ((f32x2v){wg1[j], wg1[j + 1]} * g1 + ((f32x2v){wg2[j], wg2[j + 1]} * c_g + (f32x2v){bg[j], bg[j + 1]}));
;                         const f32x2v vc = (f32x2v){wv0[j], wv0[j + 1]} * v2 + ((f32x2v){wv1[j], wv1[j + 1]} * v1 + ((f32x2v){wv2[j], wv2[j + 1]} * c_v + (f32x2v){bvv[j], bvv[j + 1]}));
;                         const f32x2v e = gc * (-1.4426950408889634f); f32x2v t; t.x = __builtin_amdgcn_exp2f(e.x); t.y = __builtin_amdgcn_exp2f(e.y);
;                         const f32x2v d = t + 1.0f; f32x2v r; r.x = __builtin_amdgcn_rcpf(d.x); r.y = __builtin_amdgcn_rcpf(d.y);
;                         const f32x2v oo = (gc * r) * vc; o[j] = oo.x; o[j + 1] = oo.y; }
;                     u32x2 w; w.x = cvt_pk_bf16(o[0], o[1]); w.y = cvt_pk_bf16(o[2], o[3]);
;                     if (hf == 0) keep[m] = w;
;                     else *(u32x4*)(A2 + (size_t)(rowb + ai * HALF + m) * FFW + c0) = (u32x4){keep[m].x, keep[m].y, w.x, w.y}; }
	v_cvt_pk_bf16_f32 v232, v214, v215
	v_cvt_pk_bf16_f32 v233, v220, v221
	global_store_dwordx4 v[210:211], v[230:233], off
	v_lshl_add_u64 v[210:211], v[210:211], 0, s[98:99]
	v_pk_fma_f32 v[214:215], v[62:63], v[146:147], v[154:155]
	v_pk_fma_f32 v[220:221], v[64:65], v[148:149], v[156:157]
	v_pk_fma_f32 v[216:217], v[58:59], v[150:151], v[158:159]
	v_pk_fma_f32 v[222:223], v[60:61], v[152:153], v[160:161]
	v_pk_fma_f32 v[214:215], v[138:139], v[90:91], v[214:215]
	v_pk_fma_f32 v[220:221], v[140:141], v[92:93], v[220:221]
	v_pk_fma_f32 v[216:217], v[142:143], v[82:83], v[216:217]
	v_pk_fma_f32 v[222:223], v[144:145], v[84:85], v[222:223]
	v_pk_fma_f32 v[214:215], v[130:131], v[106:107], v[214:215]
	v_pk_fma_f32 v[220:221], v[132:133], v[108:109], v[220:221]
	v_pk_fma_f32 v[216:217], v[134:135], v[98:99], v[216:217]
	v_pk_fma_f32 v[222:223], v[136:137], v[100:101], v[222:223]
	v_pk_mul_f32 v[218:219], v[214:215], s[88:89] op_sel_hi:[1,0]
	v_pk_mul_f32 v[224:225], v[220:221], s[88:89] op_sel_hi:[1,0]
	v_exp_f32_e32 v218, v218
	v_exp_f32_e32 v224, v224
	v_exp_f32_e32 v219, v219
	v_exp_f32_e32 v225, v225
	v_pk_add_f32 v[218:219], v[218:219], 1.0 op_sel_hi:[1,0]
	v_pk_add_f32 v[224:225], v[224:225], 1.0 op_sel_hi:[1,0]
	v_rcp_f32_e32 v218, v218
	v_rcp_f32_e32 v224, v224
	v_rcp_f32_e32 v219, v219
	v_rcp_f32_e32 v225, v225
	v_pk_mul_f32 v[214:215], v[214:215], v[218:219]
	v_pk_mul_f32 v[220:221], v[220:221], v[224:225]
	v_pk_mul_f32 v[214:215], v[216:217], v[214:215]
	v_pk_mul_f32 v[220:221], v[222:223], v[220:221]
	v_cvt_pk_bf16_f32 v236, v214, v215
	v_cvt_pk_bf16_f32 v237, v220, v221
	global_store_dwordx4 v[210:211], v[234:237], off
	v_lshl_add_u64 v[210:211], v[210:211], 0, s[98:99]
	v_pk_fma_f32 v[214:215], v[70:71], v[146:147], v[154:155]
	v_pk_fma_f32 v[220:221], v[72:73], v[148:149], v[156:157]
	v_pk_fma_f32 v[216:217], v[66:67], v[150:151], v[158:159]
	v_pk_fma_f32 v[222:223], v[68:69], v[152:153], v[160:161]
	v_pk_fma_f32 v[214:215], v[138:139], v[62:63], v[214:215]
	v_pk_fma_f32 v[220:221], v[140:141], v[64:65], v[220:221]
	v_pk_fma_f32 v[216:217], v[142:143], v[58:59], v[216:217]
	v_pk_fma_f32 v[222:223], v[144:145], v[60:61], v[222:223]
	v_pk_fma_f32 v[214:215], v[130:131], v[90:91], v[214:215]
	v_pk_fma_f32 v[220:221], v[132:133], v[92:93], v[220:221]
	v_pk_fma_f32 v[216:217], v[134:135], v[82:83], v[216:217]
	v_pk_fma_f32 v[222:223], v[136:137], v[84:85], v[222:223]
	v_pk_mul_f32 v[218:219], v[214:215], s[88:89] op_sel_hi:[1,0]
	v_pk_mul_f32 v[224:225], v[220:221], s[88:89] op_sel_hi:[1,0]
	v_exp_f32_e32 v218, v218
	v_exp_f32_e32 v224, v224
	v_exp_f32_e32 v219, v219
	v_exp_f32_e32 v225, v225
	v_pk_add_f32 v[218:219], v[218:219], 1.0 op_sel_hi:[1,0]
	v_pk_add_f32 v[224:225], v[224:225], 1.0 op_sel_hi:[1,0]
	v_rcp_f32_e32 v218, v218
	v_rcp_f32_e32 v224, v224
	v_rcp_f32_e32 v219, v219
	v_rcp_f32_e32 v225, v225
	v_pk_mul_f32 v[214:215], v[214:215], v[218:219]
	v_pk_mul_f32 v[220:221], v[220:221], v[224:225]
	v_pk_mul_f32 v[214:215], v[216:217], v[214:215]
	v_pk_mul_f32 v[220:221], v[222:223], v[220:221]
	v_cvt_pk_bf16_f32 v112, v214, v215
	v_cvt_pk_bf16_f32 v113, v220, v221
	global_store_dwordx4 v[210:211], v[110:113], off
	s_mov_b32 s98, 0xaa800
	v_lshl_add_u64 v[210:211], v[210:211], 0, s[98:99]
	s_mov_b32 s98, 0x1600
	v_lshl_add_u64 v[210:211], v[210:211], 0, s[98:99]
	ds_read_b128 v[130:133], v197 offset:0
	ds_read_b128 v[134:137], v197 offset:512
	ds_read_b128 v[138:141], v197 offset:1024
	ds_read_b128 v[142:145], v197 offset:1536
	ds_read_b128 v[146:149], v197 offset:2048
	ds_read_b128 v[150:153], v197 offset:2560
	ds_read_b128 v[154:157], v197 offset:3072
	ds_read_b128 v[158:161], v197 offset:3584
	s_and_b64 vcc, exec, s[36:37]
	s_cbranch_vccz .Lffn_hz_3
	ds_read_b128 v[162:165], v199 offset:0
	ds_read_b128 v[166:169], v199 offset:512
	ds_read_b128 v[170:173], v199 offset:1024
	ds_read_b128 v[174:177], v199 offset:1536
	s_branch .Lffn_hj_3

; __device__ __forceinline__ unsigned cvt_pk_bf16(float lo, float hi) { unsigned r; asm("v_cvt_pk_bf16_f32 %0, %1, %2" : "=v"(r) : "v"(lo), "v"(hi)); return r; }
;     __device__ __forceinline__ void operator()(f32x4 (&acc)[2][2][4][2], const Unit& u, int wr, int wc, int fr, int fq, int next_pn) const {
;     ...
;                 for (int j = 0; j < 4; ++j) { sg3[j] = dpp_shr1(hg63[j], acc[ai][0][3][hf][j]); sg2[j] = dpp_shr1(hg62[j], acc[ai][0][2][hf][j]); sv3[j] = dpp_shr1(hv63[j], acc[ai][1][3][hf][j]); sv2[j] = dpp_shr1(hv62[j], acc[ai][1][2][hf][j]); }
; #pragma unroll
;                 for (int m = 0; m < 4; ++m) {
;                     const f32x4 cg = acc[ai][0][m][hf], cv = acc[ai][1][m][hf];
;                     const f32x4 g1v = (m == 0) ? sg3 : acc[ai][0][m == 0 ? 0 : m - 1][hf], g2v = (m == 0) ? sg2 : (m == 1) ? sg3 : acc[ai][0][m < 2 ? 0 : m - 2][hf];
;                     const f32x4 v1v = (m == 0) ? sv3 : acc[ai][1][m == 0 ? 0 : m - 1][hf], v2v = (m == 0) ? sv2 : (m == 1) ? sv3 : acc[ai][1][m < 2 ? 0 : m - 2][hf];
;                     float o[4];
; #pragma unroll
;                     for (int j2 = 0; j2 < 2; ++j2) {
;                         const int j = 2 * j2;
;                         const f32x2v g1 = {g1v[j], g1v[j + 1]}, g2 = {g2v[j], g2v[j + 1]}, v1 = {v1v[j], v1v[j + 1]}, v2 = {v2v[j], v2v[j + 1]};
;                         const f32x2v c_g = {cg[j], cg[j + 1]}, c_v = {cv[j], cv[j + 1]};
;                         const f32x2v gc = (f32x2v){wg0[j], wg0[j + 1]} * g2 + ((f32x2v){wg1[j], wg1[j + 1]} * g1 + ((f32x2v){wg2[j], wg2[j + 1]} * c_g + (f32x2v){bg[j], bg[j + 1]}));
;                         const f32x2v vc = (f32x2v){wv0[j], wv0[j + 1]} * v2 + ((f32x2v){wv1[j], wv1[j + 1]} * v1 + ((f32x2v){wv2[j], wv2[j + 1]} * c_v + (f32x2v){bvv[j], bvv[j + 1]}));
;                         const f32x2v e = gc * (-1.4426950408889634f); f32x2v t; t.x = __builtin_amdgcn_exp2f(e.x); t.y = __builtin_amdgcn_exp2f(e.y);
;                         const f32x2v d = t + 1.0f; f32x2v r; r.x = __builtin_amdgcn_rcpf(d.x); r.y = __builtin_amdgcn_rcpf(d.y);
;                         const f32x2v oo = (gc * r) * vc; o[j] = oo.x; o[j + 1] = oo.y; }
;                     u32x2 w; w.x = cvt_pk_bf16(o[0], o[1]); w.y = cvt_pk_bf16(o[2], o[3]);
;                     if (hf == 0) keep[m] = w;
.Lffn_hj_3:
	s_waitcnt lgkmcnt(0)
	v_mov_b32_dpp v170, v74 row_shr:1 row_mask:0xf bank_mask:0xf
	v_mov_b32_dpp v162, v50 row_shr:1 row_mask:0xf bank_mask:0xf
	v_mov_b32_dpp v174, v78 row_shr:1 row_mask:0xf bank_mask:0xf
	v_mov_b32_dpp v166, v54 row_shr:1 row_mask:0xf bank_mask:0xf
	v_mov_b32_dpp v171, v75 row_shr:1 row_mask:0xf bank_mask:0xf
	v_mov_b32_dpp v163, v51 row_shr:1 row_mask:0xf bank_mask:0xf
	v_mov_b32_dpp v175, v79 row_shr:1 row_mask:0xf bank_mask:0xf
	v_mov_b32_dpp v167, v55 row_shr:1 row_mask:0xf bank_mask:0xf
	v_mov_b32_dpp v172, v76 row_shr:1 row_mask:0xf bank_mask:0xf
	v_mov_b32_dpp v164, v52 row_shr:1 row_mask:0xf bank_mask:0xf
	v_mov_b32_dpp v176, v80 row_shr:1 row_mask:0xf bank_mask:0xf
	v_mov_b32_dpp v168, v56 row_shr:1 row_mask:0xf bank_mask:0xf
	v_mov_b32_dpp v173, v77 row_shr:1 row_mask:0xf bank_mask:0xf
	v_mov_b32_dpp v165, v53 row_shr:1 row_mask:0xf bank_mask:0xf
	v_mov_b32_dpp v177, v81 row_shr:1 row_mask:0xf bank_mask:0xf
	v_mov_b32_dpp v169, v57 row_shr:1 row_mask:0xf bank_mask:0xf
	v_pk_fma_f32 v[214:215], v[46:47], v[146:147], v[154:155]
	v_pk_fma_f32 v[220:221], v[48:49], v[148:149], v[156:157]
	v_pk_fma_f32 v[216:217], v[42:43], v[150:151], v[158:159]
	v_pk_fma_f32 v[222:223], v[44:45], v[152:153], v[160:161]
	v_pk_fma_f32 v[214:215], v[138:139], v[170:171], v[214:215]
	v_pk_fma_f32 v[220:221], v[140:141], v[172:173], v[220:221]
	v_pk_fma_f32 v[216:217], v[142:143], v[174:175], v[216:217]
	v_pk_fma_f32 v[222:223], v[144:145], v[176:177], v[222:223]
	v_pk_fma_f32 v[214:215], v[130:131], v[162:163], v[214:215]
	v_pk_fma_f32 v[220:221], v[132:133], v[164:165], v[220:221]
	v_pk_fma_f32 v[216:217], v[134:135], v[166:167], v[216:217]
	v_pk_fma_f32 v[222:223], v[136:137], v[168:169], v[222:223]
	v_pk_mul_f32 v[218:219], v[214:215], s[88:89] op_sel_hi:[1,0]
	v_pk_mul_f32 v[224:225], v[220:221], s[88:89] op_sel_hi:[1,0]
	v_exp_f32_e32 v218, v218
	v_exp_f32_e32 v224, v224
	v_exp_f32_e32 v219, v219
	v_exp_f32_e32 v225, v225
	v_pk_add_f32 v[218:219], v[218:219], 1.0 op_sel_hi:[1,0]
	v_pk_add_f32 v[224:225], v[224:225], 1.0 op_sel_hi:[1,0]
	v_rcp_f32_e32 v218, v218
	v_rcp_f32_e32 v224, v224
	v_rcp_f32_e32 v219, v219
	v_rcp_f32_e32 v225, v225
	v_pk_mul_f32 v[214:215], v[214:215], v[218:219]
	v_pk_mul_f32 v[220:221], v[220:221], v[224:225]
	v_pk_mul_f32 v[214:215], v[216:217], v[214:215]
	v_pk_mul_f32 v[220:221], v[222:223], v[220:221]
	v_cvt_pk_bf16_f32 v226, v214, v215
	v_cvt_pk_bf16_f32 v227, v220, v221
	v_pk_fma_f32 v[214:215], v[38:39], v[146:147], v[154:155]
	v_pk_fma_f32 v[220:221], v[40:41], v[148:149], v[156:157]
	v_pk_fma_f32 v[216:217], v[26:27], v[150:151], v[158:159]
	v_pk_fma_f32 v[222:223], v[28:29], v[152:153], v[160:161]
	v_pk_fma_f32 v[214:215], v[138:139], v[46:47], v[214:215]
	v_pk_fma_f32 v[220:221], v[140:141], v[48:49], v[220:221]
	v_pk_fma_f32 v[216:217], v[142:143], v[42:43], v[216:217]
	v_pk_fma_f32 v[222:223], v[144:145], v[44:45], v[222:223]
	v_pk_fma_f32 v[214:215], v[130:131], v[170:171], v[214:215]
	v_pk_fma_f32 v[220:221], v[132:133], v[172:173], v[220:221]
	v_pk_fma_f32 v[216:217], v[134:135], v[174:175], v[216:217]
	v_pk_fma_f32 v[222:223], v[136:137], v[176:177], v[222:223]
	v_pk_mul_f32 v[218:219], v[214:215], s[88:89] op_sel_hi:[1,0]
	v_pk_mul_f32 v[224:225], v[220:221], s[88:89] op_sel_hi:[1,0]
	v_exp_f32_e32 v218, v218
	v_exp_f32_e32 v224, v224
	v_exp_f32_e32 v219, v219
	v_exp_f32_e32 v225, v225
	v_pk_add_f32 v[218:219], v[218:219], 1.0 op_sel_hi:[1,0]
	v_pk_add_f32 v[224:225], v[224:225], 1.0 op_sel_hi:[1,0]
	v_rcp_f32_e32 v218, v218
	v_rcp_f32_e32 v224, v224
	v_rcp_f32_e32 v219, v219
	v_rcp_f32_e32 v225, v225
	v_pk_mul_f32 v[214:215], v[214:215], v[218:219]
;     __device__ __forceinline__ void operator()(f32x4 (&acc)[2][2][4][2], const Unit& u, int wr, int wc, int fr, int fq, int next_pn) const {
;     ...
;             for (int hf = 0; hf < 2; ++hf) {
;                 __builtin_amdgcn_sched_barrier(0);
;                 const LAS float* wl = WL + tcol + 4 * hf;
;                 const f32x4 wg0 = *(const LAS f32x4*)(wl), wg1 = *(const LAS f32x4*)(wl + 256), wg2 = *(const LAS f32x4*)(wl + 512), bg = *(const LAS f32x4*)(wl + 768);
;     ...
; #pragma unroll
;                 for (int m = 0; m < 4; ++m) {
;                     const f32x4 cg = acc[ai][0][m][hf], cv = acc[ai][1][m][hf];
;                     const f32x4 g1v = (m == 0) ? sg3 : acc[ai][0][m == 0 ? 0 : m - 1][hf], g2v = (m == 0) ? sg2 : (m == 1) ? sg3 : acc[ai][0][m < 2 ? 0 : m - 2][hf];
;                     const f32x4 v1v = (m == 0) ? sv3 : acc[ai][1][m == 0 ? 0 : m - 1][hf], v2v = (m == 0) ? sv2 : (m == 1) ? sv3 : acc[ai][1][m < 2 ? 0 : m - 2][hf];
;                     float o[4];
; #pragma unroll
;                     for (int j2 = 0; j2 < 2; ++j2) {
;                         const int j = 2 * j2;
;                         const f32x2v g1 = {g1v[j], g1v[j + 1]}, g2 = {g2v[j], g2v[j + 1]}, v1 = {v1v[j], v1v[j + 1]}, v2 = {v2v[j], v2v[j + 1]};
;                         const f32x2v c_g = {cg[j], cg[j + 1]}, c_v = {cv[j], cv[j + 1]};
;                         const f32x2v gc = (f32x2v){wg0[j], wg0[j + 1]} * g2 + ((f32x2v){wg1[j], wg1[j + 1]} * g1 + ((f32x2v){wg2[j], wg2[j + 1]} * c_g + (f32x2v){bg[j], bg[j + 1]}));
;                         const f32x2v vc = (f32x2v){wv0[j], wv0[j + 1]} * v2 + ((f32x2v){wv1[j], wv1[j + 1]} * v1 + ((f32x2v){wv2[j], wv2[j + 1]} * c_v + (f32x2v){bvv[j], bvv[j + 1]}));
;                         const f32x2v e = gc * (-1.4426950408889634f); f32x2v t; t.x = __builtin_amdgcn_exp2f(e.x); t.y = __builtin_amdgcn_exp2f(e.y);
;                         const f32x2v d = t + 1.0f; f32x2v r; r.x = __builtin_amdgcn_rcpf(d.x); r.y = __builtin_amdgcn_rcpf(d.y);
;                         const f32x2v oo = (gc * r) * vc; o[j] = oo.x; o[j + 1] = oo.y; }
;                     u32x2 w; w.x = cvt_pk_bf16(o[0], o[1]); w.y = cvt_pk_bf16(o[2], o[3]);
;                     if (hf == 0) keep[m] = w;
;                     else *(u32x4*)(A2 + (size_t)(rowb + ai * HALF + m) * FFW + c0) = (u32x4){keep[m].x, keep[m].y, w.x, w.y}; }
	v_pk_mul_f32 v[220:221], v[220:221], v[224:225]
	v_pk_mul_f32 v[214:215], v[216:217], v[214:215]
	v_pk_mul_f32 v[220:221], v[222:223], v[220:221]
	v_cvt_pk_bf16_f32 v230, v214, v215
	v_cvt_pk_bf16_f32 v231, v220, v221
	v_pk_fma_f32 v[214:215], v[50:51], v[146:147], v[154:155]
	v_pk_fma_f32 v[220:221], v[52:53], v[148:149], v[156:157]
	v_pk_fma_f32 v[216:217], v[54:55], v[150:151], v[158:159]
	v_pk_fma_f32 v[222:223], v[56:57], v[152:153], v[160:161]
	v_pk_fma_f32 v[214:215], v[138:139], v[38:39], v[214:215]
	v_pk_fma_f32 v[220:221], v[140:141], v[40:41], v[220:221]
	v_pk_fma_f32 v[216:217], v[142:143], v[26:27], v[216:217]
	v_pk_fma_f32 v[222:223], v[144:145], v[28:29], v[222:223]
	v_pk_fma_f32 v[214:215], v[130:131], v[46:47], v[214:215]
	v_pk_fma_f32 v[220:221], v[132:133], v[48:49], v[220:221]
	v_pk_fma_f32 v[216:217], v[134:135], v[42:43], v[216:217]
	v_pk_fma_f32 v[222:223], v[136:137], v[44:45], v[222:223]
	v_pk_mul_f32 v[218:219], v[214:215], s[88:89] op_sel_hi:[1,0]
	v_pk_mul_f32 v[224:225], v[220:221], s[88:89] op_sel_hi:[1,0]
	v_exp_f32_e32 v218, v218
	v_exp_f32_e32 v224, v224
	v_exp_f32_e32 v219, v219
	v_exp_f32_e32 v225, v225
	v_pk_add_f32 v[218:219], v[218:219], 1.0 op_sel_hi:[1,0]
	v_pk_add_f32 v[224:225], v[224:225], 1.0 op_sel_hi:[1,0]
	v_rcp_f32_e32 v218, v218
	v_rcp_f32_e32 v224, v224
	v_rcp_f32_e32 v219, v219
	v_rcp_f32_e32 v225, v225
	v_pk_mul_f32 v[214:215], v[214:215], v[218:219]
	v_pk_mul_f32 v[220:221], v[220:221], v[224:225]
	v_pk_mul_f32 v[214:215], v[216:217], v[214:215]
	v_pk_mul_f32 v[220:221], v[222:223], v[220:221]
	v_cvt_pk_bf16_f32 v234, v214, v215
	v_cvt_pk_bf16_f32 v235, v220, v221
	v_pk_fma_f32 v[214:215], v[74:75], v[146:147], v[154:155]
	v_pk_fma_f32 v[220:221], v[76:77], v[148:149], v[156:157]
	v_pk_fma_f32 v[216:217], v[78:79], v[150:151], v[158:159]
	v_pk_fma_f32 v[222:223], v[80:81], v[152:153], v[160:161]
	v_pk_fma_f32 v[214:215], v[138:139], v[50:51], v[214:215]
	v_pk_fma_f32 v[220:221], v[140:141], v[52:53], v[220:221]
	v_pk_fma_f32 v[216:217], v[142:143], v[54:55], v[216:217]
	v_pk_fma_f32 v[222:223], v[144:145], v[56:57], v[222:223]
	v_pk_fma_f32 v[214:215], v[130:131], v[38:39], v[214:215]
	v_pk_fma_f32 v[220:221], v[132:133], v[40:41], v[220:221]
	v_pk_fma_f32 v[216:217], v[134:135], v[26:27], v[216:217]
	v_pk_fma_f32 v[222:223], v[136:137], v[28:29], v[222:223]
	v_pk_mul_f32 v[218:219], v[214:215], s[88:89] op_sel_hi:[1,0]
	v_pk_mul_f32 v[224:225], v[220:221], s[88:89] op_sel_hi:[1,0]
	v_exp_f32_e32 v218, v218
	v_exp_f32_e32 v224, v224
	v_exp_f32_e32 v219, v219
	v_exp_f32_e32 v225, v225
	v_pk_add_f32 v[218:219], v[218:219], 1.0 op_sel_hi:[1,0]
	v_pk_add_f32 v[224:225], v[224:225], 1.0 op_sel_hi:[1,0]
	v_rcp_f32_e32 v218, v218
	v_rcp_f32_e32 v224, v224
	v_rcp_f32_e32 v219, v219
	v_rcp_f32_e32 v225, v225
	v_pk_mul_f32 v[214:215], v[214:215], v[218:219]
	v_pk_mul_f32 v[220:221], v[220:221], v[224:225]
	v_pk_mul_f32 v[214:215], v[216:217], v[214:215]
	v_pk_mul_f32 v[220:221], v[222:223], v[220:221]
	v_cvt_pk_bf16_f32 v46, v214, v215
	v_cvt_pk_bf16_f32 v47, v220, v221
	ds_read_b128 v[130:133], v197 offset:16
	ds_read_b128 v[134:137], v197 offset:528
	ds_read_b128 v[138:141], v197 offset:1040
	ds_read_b128 v[142:145], v197 offset:1552
	ds_read_b128 v[146:149], v197 offset:2064
	ds_read_b128 v[150:153], v197 offset:2576
	ds_read_b128 v[154:157], v197 offset:3088
	ds_read_b128 v[158:161], v197 offset:3600
	s_and_b64 vcc, exec, s[36:37]
	s_cbranch_vccz .Lffn_hz_4
	ds_read_b128 v[162:165], v199 offset:16
	ds_read_b128 v[166:169], v199 offset:528
	ds_read_b128 v[170:173], v199 offset:1040
	ds_read_b128 v[174:177], v199 offset:1552
	s_branch .Lffn_hj_4

;     __device__ __forceinline__ void operator()(f32x4 (&acc)[2][2][4][2], const Unit& u, int wr, int wc, int fr, int fq, int next_pn) const {
;     ...
;                 for (int j = 0; j < 4; ++j) { sg3[j] = dpp_shr1(hg63[j], acc[ai][0][3][hf][j]); sg2[j] = dpp_shr1(hg62[j], acc[ai][0][2][hf][j]); sv3[j] = dpp_shr1(hv63[j], acc[ai][1][3][hf][j]); sv2[j] = dpp_shr1(hv62[j], acc[ai][1][2][hf][j]); }
; #pragma unroll
;                 for (int m = 0; m < 4; ++m) {
;                     const f32x4 cg = acc[ai][0][m][hf], cv = acc[ai][1][m][hf];
;                     const f32x4 g1v = (m == 0) ? sg3 : acc[ai][0][m == 0 ? 0 : m - 1][hf], g2v = (m == 0) ? sg2 : (m == 1) ? sg3 : acc[ai][0][m < 2 ? 0 : m - 2][hf];
;                     const f32x4 v1v = (m == 0) ? sv3 : acc[ai][1][m == 0 ? 0 : m - 1][hf], v2v = (m == 0) ? sv2 : (m == 1) ? sv3 : acc[ai][1][m < 2 ? 0 : m - 2][hf];
;                     float o[4];
; #pragma unroll
;                     for (int j2 = 0; j2 < 2; ++j2) {
;                         const int j = 2 * j2;
;                         const f32x2v g1 = {g1v[j], g1v[j + 1]}, g2 = {g2v[j], g2v[j + 1]}, v1 = {v1v[j], v1v[j + 1]}, v2 = {v2v[j], v2v[j + 1]};
;                         const f32x2v c_g = {cg[j], cg[j + 1]}, c_v = {cv[j], cv[j + 1]};
;                         const f32x2v gc = (f32x2v){wg0[j], wg0[j + 1]} * g2 + ((f32x2v){wg1[j], wg1[j + 1]} * g1 + ((f32x2v){wg2[j], wg2[j + 1]} * c_g + (f32x2v){bg[j], bg[j + 1]}));
;                         const f32x2v vc = (f32x2v){wv0[j], wv0[j + 1]} * v2 + ((f32x2v){wv1[j], wv1[j + 1]} * v1 + ((f32x2v){wv2[j], wv2[j + 1]} * c_v + (f32x2v){bvv[j], bvv[j + 1]}));
;                         const f32x2v e = gc * (-1.4426950408889634f); f32x2v t; t.x = __builtin_amdgcn_exp2f(e.x); t.y = __builtin_amdgcn_exp2f(e.y);
;                         const f32x2v d = t + 1.0f; f32x2v r; r.x = __builtin_amdgcn_rcpf(d.x); r.y = __builtin_amdgcn_rcpf(d.y);
;                         const f32x2v oo = (gc * r) * vc; o[j] = oo.x; o[j + 1] = oo.y; }
;                     u32x2 w; w.x = cvt_pk_bf16(o[0], o[1]); w.y = cvt_pk_bf16(o[2], o[3]);
;                     if (hf == 0) keep[m] = w;
;                     else *(u32x4*)(A2 + (size_t)(rowb + ai * HALF + m) * FFW + c0) = (u32x4){keep[m].x, keep[m].y, w.x, w.y}; }
.Lffn_hj_4:
	s_waitcnt lgkmcnt(0)
	v_mov_b32_dpp v170, v10 row_shr:1 row_mask:0xf bank_mask:0xf
	v_mov_b32_dpp v162, v2 row_shr:1 row_mask:0xf bank_mask:0xf
	v_mov_b32_dpp v174, v14 row_shr:1 row_mask:0xf bank_mask:0xf
	v_mov_b32_dpp v166, v6 row_shr:1 row_mask:0xf bank_mask:0xf
	v_mov_b32_dpp v171, v11 row_shr:1 row_mask:0xf bank_mask:0xf
	v_mov_b32_dpp v163, v3 row_shr:1 row_mask:0xf bank_mask:0xf
	v_mov_b32_dpp v175, v15 row_shr:1 row_mask:0xf bank_mask:0xf
	v_mov_b32_dpp v167, v7 row_shr:1 row_mask:0xf bank_mask:0xf
	v_mov_b32_dpp v172, v12 row_shr:1 row_mask:0xf bank_mask:0xf
	v_mov_b32_dpp v164, v4 row_shr:1 row_mask:0xf bank_mask:0xf
	v_mov_b32_dpp v176, v16 row_shr:1 row_mask:0xf bank_mask:0xf
	v_mov_b32_dpp v168, v8 row_shr:1 row_mask:0xf bank_mask:0xf
	v_mov_b32_dpp v173, v13 row_shr:1 row_mask:0xf bank_mask:0xf
	v_mov_b32_dpp v165, v5 row_shr:1 row_mask:0xf bank_mask:0xf
	v_mov_b32_dpp v177, v17 row_shr:1 row_mask:0xf bank_mask:0xf
	v_mov_b32_dpp v169, v9 row_shr:1 row_mask:0xf bank_mask:0xf
	v_pk_fma_f32 v[214:215], v[30:31], v[146:147], v[154:155]
	v_pk_fma_f32 v[220:221], v[32:33], v[148:149], v[156:157]
	v_pk_fma_f32 v[216:217], v[34:35], v[150:151], v[158:159]
	v_pk_fma_f32 v[222:223], v[36:37], v[152:153], v[160:161]
	v_pk_fma_f32 v[214:215], v[138:139], v[170:171], v[214:215]
	v_pk_fma_f32 v[220:221], v[140:141], v[172:173], v[220:221]
	v_pk_fma_f32 v[216:217], v[142:143], v[174:175], v[216:217]
	v_pk_fma_f32 v[222:223], v[144:145], v[176:177], v[222:223]
	v_pk_fma_f32 v[214:215], v[130:131], v[162:163], v[214:215]
	v_pk_fma_f32 v[220:221], v[132:133], v[164:165], v[220:221]
	v_pk_fma_f32 v[216:217], v[134:135], v[166:167], v[216:217]
	v_pk_fma_f32 v[222:223], v[136:137], v[168:169], v[222:223]
	v_pk_mul_f32 v[218:219], v[214:215], s[88:89] op_sel_hi:[1,0]
	v_pk_mul_f32 v[224:225], v[220:221], s[88:89] op_sel_hi:[1,0]
	v_exp_f32_e32 v218, v218
	v_exp_f32_e32 v224, v224
	v_exp_f32_e32 v219, v219
	v_exp_f32_e32 v225, v225
	v_pk_add_f32 v[218:219], v[218:219], 1.0 op_sel_hi:[1,0]
	v_pk_add_f32 v[224:225], v[224:225], 1.0 op_sel_hi:[1,0]
	v_rcp_f32_e32 v218, v218
	v_rcp_f32_e32 v224, v224
	v_rcp_f32_e32 v219, v219
	v_rcp_f32_e32 v225, v225
	v_pk_mul_f32 v[214:215], v[214:215], v[218:219]
	v_pk_mul_f32 v[220:221], v[220:221], v[224:225]
	v_pk_mul_f32 v[214:215], v[216:217], v[214:215]
	v_pk_mul_f32 v[220:221], v[222:223], v[220:221]
	v_cvt_pk_bf16_f32 v228, v214, v215
	v_cvt_pk_bf16_f32 v229, v220, v221
	global_store_dwordx4 v[210:211], v[226:229], off
	v_lshl_add_u64 v[210:211], v[210:211], 0, s[98:99]
	v_pk_fma_f32 v[214:215], v[18:19], v[146:147], v[154:155]
	v_pk_fma_f32 v[220:221], v[20:21], v[148:149], v[156:157]
	v_pk_fma_f32 v[216:217], v[22:23], v[150:151], v[158:159]
	v_pk_fma_f32 v[222:223], v[24:25], v[152:153], v[160:161]
	v_pk_fma_f32 v[214:215], v[138:139], v[30:31], v[214:215]
	v_pk_fma_f32 v[220:221], v[140:141], v[32:33], v[220:221]
	v_pk_fma_f32 v[216:217], v[142:143], v[34:35], v[216:217]
	v_pk_fma_f32 v[222:223], v[144:145], v[36:37], v[222:223]
	v_pk_fma_f32 v[214:215], v[130:131], v[170:171], v[214:215]
	v_pk_fma_f32 v[220:221], v[132:133], v[172:173], v[220:221]
	v_pk_fma_f32 v[216:217], v[134:135], v[174:175], v[216:217]
	v_pk_fma_f32 v[222:223], v[136:137], v[176:177], v[222:223]
	v_pk_mul_f32 v[218:219], v[214:215], s[88:89] op_sel_hi:[1,0]
	v_pk_mul_f32 v[224:225], v[220:221], s[88:89] op_sel_hi:[1,0]
	v_exp_f32_e32 v218, v218
	v_exp_f32_e32 v224, v224
	v_exp_f32_e32 v219, v219
	v_exp_f32_e32 v225, v225
	v_pk_add_f32 v[218:219], v[218:219], 1.0 op_sel_hi:[1,0]
	v_pk_add_f32 v[224:225], v[224:225], 1.0 op_sel_hi:[1,0]
	v_rcp_f32_e32 v218, v218
	v_rcp_f32_e32 v224, v224
; #define LAS __attribute__((address_space(3)))
; __device__ __forceinline__ unsigned cvt_pk_bf16(float lo, float hi) { unsigned r; asm("v_cvt_pk_bf16_f32 %0, %1, %2" : "=v"(r) : "v"(lo), "v"(hi)); return r; }
;     __device__ __forceinline__ void operator()(f32x4 (&acc)[2][2][4][2], const Unit& u, int wr, int wc, int fr, int fq, int next_pn) const {
;     ...
;                 for (int m = 0; m < 4; ++m) {
;                     const f32x4 cg = acc[ai][0][m][hf], cv = acc[ai][1][m][hf];
;                     const f32x4 g1v = (m == 0) ? sg3 : acc[ai][0][m == 0 ? 0 : m - 1][hf], g2v = (m == 0) ? sg2 : (m == 1) ? sg3 : acc[ai][0][m < 2 ? 0 : m - 2][hf];
;                     const f32x4 v1v = (m == 0) ? sv3 : acc[ai][1][m == 0 ? 0 : m - 1][hf], v2v = (m == 0) ? sv2 : (m == 1) ? sv3 : acc[ai][1][m < 2 ? 0 : m - 2][hf];
;                     float o[4];
; #pragma unroll
;                     for (int j2 = 0; j2 < 2; ++j2) {
;                         const int j = 2 * j2;
;                         const f32x2v g1 = {g1v[j], g1v[j + 1]}, g2 = {g2v[j], g2v[j + 1]}, v1 = {v1v[j], v1v[j + 1]}, v2 = {v2v[j], v2v[j + 1]};
;                         const f32x2v c_g = {cg[j], cg[j + 1]}, c_v = {cv[j], cv[j + 1]};
;                         const f32x2v gc = (f32x2v){wg0[j], wg0[j + 1]} * g2 + ((f32x2v){wg1[j], wg1[j + 1]} * g1 + ((f32x2v){wg2[j], wg2[j + 1]} * c_g + (f32x2v){bg[j], bg[j + 1]}));
;                         const f32x2v vc = (f32x2v){wv0[j], wv0[j + 1]} * v2 + ((f32x2v){wv1[j], wv1[j + 1]} * v1 + ((f32x2v){wv2[j], wv2[j + 1]} * c_v + (f32x2v){bvv[j], bvv[j + 1]}));
;                         const f32x2v e = gc * (-1.4426950408889634f); f32x2v t; t.x = __builtin_amdgcn_exp2f(e.x); t.y = __builtin_amdgcn_exp2f(e.y);
;                         const f32x2v d = t + 1.0f; f32x2v r; r.x = __builtin_amdgcn_rcpf(d.x); r.y = __builtin_amdgcn_rcpf(d.y);
;                         const f32x2v oo = (gc * r) * vc; o[j] = oo.x; o[j + 1] = oo.y; }
;                     u32x2 w; w.x = cvt_pk_bf16(o[0], o[1]); w.y = cvt_pk_bf16(o[2], o[3]);
;                     if (hf == 0) keep[m] = w;
;                     else *(u32x4*)(A2 + (size_t)(rowb + ai * HALF + m) * FFW + c0) = (u32x4){keep[m].x, keep[m].y, w.x, w.y}; }
;             }
;             __builtin_amdgcn_sched_barrier(0);
;         }
;         if (next_pn >= 0) { *(LAS f32x2v*)(WL0 + (1 - bcur) * 1024 + wl_idx) = wn2; }
	v_rcp_f32_e32 v219, v219
	v_rcp_f32_e32 v225, v225
	v_pk_mul_f32 v[214:215], v[214:215], v[218:219]
	v_pk_mul_f32 v[220:221], v[220:221], v[224:225]
	v_pk_mul_f32 v[214:215], v[216:217], v[214:215]
	v_pk_mul_f32 v[220:221], v[222:223], v[220:221]
	v_cvt_pk_bf16_f32 v232, v214, v215
	v_cvt_pk_bf16_f32 v233, v220, v221
	global_store_dwordx4 v[210:211], v[230:233], off
	v_lshl_add_u64 v[210:211], v[210:211], 0, s[98:99]
	v_pk_fma_f32 v[214:215], v[2:3], v[146:147], v[154:155]
	v_pk_fma_f32 v[220:221], v[4:5], v[148:149], v[156:157]
	v_pk_fma_f32 v[216:217], v[6:7], v[150:151], v[158:159]
	v_pk_fma_f32 v[222:223], v[8:9], v[152:153], v[160:161]
	v_pk_fma_f32 v[214:215], v[138:139], v[18:19], v[214:215]
	v_pk_fma_f32 v[220:221], v[140:141], v[20:21], v[220:221]
	v_pk_fma_f32 v[216:217], v[142:143], v[22:23], v[216:217]
	v_pk_fma_f32 v[222:223], v[144:145], v[24:25], v[222:223]
	v_pk_fma_f32 v[214:215], v[130:131], v[30:31], v[214:215]
	v_pk_fma_f32 v[220:221], v[132:133], v[32:33], v[220:221]
	v_pk_fma_f32 v[216:217], v[134:135], v[34:35], v[216:217]
	v_pk_fma_f32 v[222:223], v[136:137], v[36:37], v[222:223]
	v_pk_mul_f32 v[218:219], v[214:215], s[88:89] op_sel_hi:[1,0]
	v_pk_mul_f32 v[224:225], v[220:221], s[88:89] op_sel_hi:[1,0]
	v_exp_f32_e32 v218, v218
	v_exp_f32_e32 v224, v224
	v_exp_f32_e32 v219, v219
	v_exp_f32_e32 v225, v225
	v_pk_add_f32 v[218:219], v[218:219], 1.0 op_sel_hi:[1,0]
	v_pk_add_f32 v[224:225], v[224:225], 1.0 op_sel_hi:[1,0]
	v_rcp_f32_e32 v218, v218
	v_rcp_f32_e32 v224, v224
	v_rcp_f32_e32 v219, v219
	v_rcp_f32_e32 v225, v225
	v_pk_mul_f32 v[214:215], v[214:215], v[218:219]
	v_pk_mul_f32 v[220:221], v[220:221], v[224:225]
	v_pk_mul_f32 v[214:215], v[216:217], v[214:215]
	v_pk_mul_f32 v[220:221], v[222:223], v[220:221]
	v_cvt_pk_bf16_f32 v236, v214, v215
	v_cvt_pk_bf16_f32 v237, v220, v221
	global_store_dwordx4 v[210:211], v[234:237], off
	v_lshl_add_u64 v[210:211], v[210:211], 0, s[98:99]
	v_pk_fma_f32 v[214:215], v[10:11], v[146:147], v[154:155]
	v_pk_fma_f32 v[220:221], v[12:13], v[148:149], v[156:157]
	v_pk_fma_f32 v[216:217], v[14:15], v[150:151], v[158:159]
	v_pk_fma_f32 v[222:223], v[16:17], v[152:153], v[160:161]
	v_pk_fma_f32 v[214:215], v[138:139], v[2:3], v[214:215]
	v_pk_fma_f32 v[220:221], v[140:141], v[4:5], v[220:221]
	v_pk_fma_f32 v[216:217], v[142:143], v[6:7], v[216:217]
	v_pk_fma_f32 v[222:223], v[144:145], v[8:9], v[222:223]
	v_pk_fma_f32 v[214:215], v[130:131], v[18:19], v[214:215]
	v_pk_fma_f32 v[220:221], v[132:133], v[20:21], v[220:221]
	v_pk_fma_f32 v[216:217], v[134:135], v[22:23], v[216:217]
	v_pk_fma_f32 v[222:223], v[136:137], v[24:25], v[222:223]
	v_pk_mul_f32 v[218:219], v[214:215], s[88:89] op_sel_hi:[1,0]
	v_pk_mul_f32 v[224:225], v[220:221], s[88:89] op_sel_hi:[1,0]
	v_exp_f32_e32 v218, v218
	v_exp_f32_e32 v224, v224
	v_exp_f32_e32 v219, v219
	v_exp_f32_e32 v225, v225
	v_pk_add_f32 v[218:219], v[218:219], 1.0 op_sel_hi:[1,0]
	v_pk_add_f32 v[224:225], v[224:225], 1.0 op_sel_hi:[1,0]
	v_rcp_f32_e32 v218, v218
	v_rcp_f32_e32 v224, v224
	v_rcp_f32_e32 v219, v219
	v_rcp_f32_e32 v225, v225
	v_pk_mul_f32 v[214:215], v[214:215], v[218:219]
	v_pk_mul_f32 v[220:221], v[220:221], v[224:225]
	v_pk_mul_f32 v[214:215], v[216:217], v[214:215]
	v_pk_mul_f32 v[220:221], v[222:223], v[220:221]
	v_cvt_pk_bf16_f32 v48, v214, v215
	v_cvt_pk_bf16_f32 v49, v220, v221
	global_store_dwordx4 v[210:211], v[46:49], off
	s_andn2_b64 vcc, exec, s[42:43]
	s_cbranch_vccnz .LBB0_747
	s_and_b64 s[8:9], s[6:7], exec
	s_cselect_b32 s8, 0, 0x1000
	s_add_i32 s8, s8, 0
	v_lshl_add_u32 v0, v208, 2, s8
	v_add_u32_e32 v0, 0x22100, v0
	s_waitcnt vmcnt(8)
	ds_write_b64 v0, v[192:193]
